# grid barrier: XCD leaders poll the TOP arrival counter directly (TOP >= target) instead of waiting for the last leader's TOPGEN bump
# speedup vs baseline: 1.0196x; 1.0033x over previous
; __device__ __forceinline__ unsigned xb_ld(unsigned* p)              { return __hip_atomic_load(p, __ATOMIC_RELAXED, __HIP_MEMORY_SCOPE_AGENT); }
; __device__ __forceinline__ unsigned xb_add(unsigned* p, unsigned v) { return __hip_atomic_fetch_add(p, v, __ATOMIC_RELAXED, __HIP_MEMORY_SCOPE_AGENT); }
; #define XB_SPIN(cond, bar) do { unsigned _sp = 0; while (cond) { \
;     if ((++_sp & 255u) == 0u) { if (xb_ld(&(bar)[XB_TMO])) break; if (_sp > XB_SPIN_CAP) { atomicAdd(&(bar)[XB_TMO], 1u); break; } } } } while (0)
; __device__ __forceinline__ void xcd_barrier(const XcdBarrier& b) {
;     ...
;             const unsigned og = xb_add(&bar[XB_TOP], 1u);
;             const unsigned tg = og / nx;
;             if (og + 1u == (tg + 1u) * nx) xb_add(&bar[XB_TOPGEN], 1u);
;             else XB_SPIN(xb_ld(&bar[XB_TOPGEN]) == tg, bar);
.LBB0_215:
	s_or_b64 exec, exec, s[8:9]
	v_cvt_f32_u32_e32 v3, v0
	s_waitcnt vmcnt(0)
	v_readfirstlane_b32 s6, v2
	s_mov_b64 s[8:9], -1
	v_rcp_iflag_f32_e32 v3, v3
	v_add_u32_e32 v1, s6, v1
	v_add_u32_e32 v4, 1, v1
	v_readlane_b32 s6, v253, 62
	v_mul_f32_e32 v2, 0x4f7ffffe, v3
	v_cvt_u32_f32_e32 v2, v2
	v_sub_u32_e32 v3, 0, v0
	v_readlane_b32 s7, v253, 63
	v_mul_lo_u32 v3, v3, v2
	v_mul_hi_u32 v3, v2, v3
	v_add_u32_e32 v2, v2, v3
	v_mul_hi_u32 v2, v1, v2
	v_mul_lo_u32 v3, v2, v0
	v_sub_u32_e32 v1, v1, v3
	v_add_u32_e32 v5, 1, v2
	v_cmp_ge_u32_e32 vcc, v1, v0
	v_sub_u32_e32 v3, v1, v0
	s_nop 0
	v_cndmask_b32_e32 v2, v2, v5, vcc
	v_cndmask_b32_e32 v1, v1, v3, vcc
	v_add_u32_e32 v3, 1, v2
	v_cmp_ge_u32_e32 vcc, v1, v0
	s_nop 1
	v_cndmask_b32_e32 v2, v2, v3, vcc
	v_mul_lo_u32 v1, v0, v2
	v_add_u32_e32 v0, v1, v0
	v_cmp_ne_u32_e32 vcc, v4, v0
	v_mov_b32_e32 v5, v0
	v_mov_b64_e32 v[0:1], s[6:7]
	s_and_saveexec_b64 s[6:7], vcc
	s_cbranch_execz .LBB0_227
	v_readlane_b32 s8, v253, 60
	v_readlane_b32 s9, v253, 61
	s_mov_b64 s[10:11], 0
	s_nop 3
	global_load_dword v0, v161, s[8:9] sc1
	s_waitcnt vmcnt(0)
	v_cmp_lt_u32_e32 vcc, v0, v5
	s_and_saveexec_b64 s[8:9], vcc
	s_cbranch_execz .LBB0_226
	s_mov_b32 s20, 1
	s_branch .LBB0_219

; __device__ __forceinline__ unsigned xb_ld(unsigned* p)              { return __hip_atomic_load(p, __ATOMIC_RELAXED, __HIP_MEMORY_SCOPE_AGENT); }
; #define XB_SPIN(cond, bar) do { unsigned _sp = 0; while (cond) { \
;     if ((++_sp & 255u) == 0u) { if (xb_ld(&(bar)[XB_TMO])) break; if (_sp > XB_SPIN_CAP) { atomicAdd(&(bar)[XB_TMO], 1u); break; } } } } while (0)
; __device__ __forceinline__ void xcd_barrier(const XcdBarrier& b) {
;     ...
;             else XB_SPIN(xb_ld(&bar[XB_TOPGEN]) == tg, bar);
.LBB0_221:
	v_readlane_b32 s14, v253, 60
	v_readlane_b32 s15, v253, 61
	s_add_i32 s20, s20, 1
	s_mov_b64 s[34:35], -1
	s_nop 2
	global_load_dword v0, v161, s[14:15] sc1
	s_waitcnt vmcnt(0)
	v_cmp_ge_u32_e32 vcc, v0, v5
	s_orn2_b64 s[14:15], vcc, exec
	s_branch .LBB0_218

; __device__ __forceinline__ unsigned xb_ld(unsigned* p)              { return __hip_atomic_load(p, __ATOMIC_RELAXED, __HIP_MEMORY_SCOPE_AGENT); }
; __device__ __forceinline__ unsigned xb_add(unsigned* p, unsigned v) { return __hip_atomic_fetch_add(p, v, __ATOMIC_RELAXED, __HIP_MEMORY_SCOPE_AGENT); }
; #define XB_SPIN(cond, bar) do { unsigned _sp = 0; while (cond) { \
;     if ((++_sp & 255u) == 0u) { if (xb_ld(&(bar)[XB_TMO])) break; if (_sp > XB_SPIN_CAP) { atomicAdd(&(bar)[XB_TMO], 1u); break; } } } } while (0)
; __device__ __forceinline__ void xcd_barrier(const XcdBarrier& b) {
;     ...
;             const unsigned og = xb_add(&bar[XB_TOP], 1u);
;             const unsigned tg = og / nx;
;             if (og + 1u == (tg + 1u) * nx) xb_add(&bar[XB_TOPGEN], 1u);
;             else XB_SPIN(xb_ld(&bar[XB_TOPGEN]) == tg, bar);
.LBB0_651:
	s_or_b64 exec, exec, s[10:11]
	v_cvt_f32_u32_e32 v3, v0
	s_waitcnt vmcnt(0)
	v_readfirstlane_b32 s8, v2
	s_mov_b64 s[10:11], -1
	v_rcp_iflag_f32_e32 v3, v3
	v_add_u32_e32 v1, s8, v1
	v_add_u32_e32 v4, 1, v1
	v_readlane_b32 s8, v253, 62
	v_mul_f32_e32 v2, 0x4f7ffffe, v3
	v_cvt_u32_f32_e32 v2, v2
	v_sub_u32_e32 v3, 0, v0
	v_readlane_b32 s9, v253, 63
	v_mul_lo_u32 v3, v3, v2
	v_mul_hi_u32 v3, v2, v3
	v_add_u32_e32 v2, v2, v3
	v_mul_hi_u32 v2, v1, v2
	v_mul_lo_u32 v3, v2, v0
	v_sub_u32_e32 v1, v1, v3
	v_add_u32_e32 v5, 1, v2
	v_cmp_ge_u32_e32 vcc, v1, v0
	v_sub_u32_e32 v3, v1, v0
	s_nop 0
	v_cndmask_b32_e32 v2, v2, v5, vcc
	v_cndmask_b32_e32 v1, v1, v3, vcc
	v_add_u32_e32 v3, 1, v2
	v_cmp_ge_u32_e32 vcc, v1, v0
	s_nop 1
	v_cndmask_b32_e32 v2, v2, v3, vcc
	v_mul_lo_u32 v1, v0, v2
	v_add_u32_e32 v0, v1, v0
	v_cmp_ne_u32_e32 vcc, v4, v0
	v_mov_b32_e32 v5, v0
	v_mov_b64_e32 v[0:1], s[8:9]
	s_and_saveexec_b64 s[8:9], vcc
	s_cbranch_execz .LBB0_663
	v_readlane_b32 s10, v253, 60
	v_readlane_b32 s11, v253, 61
	s_mov_b64 s[12:13], 0
	s_nop 3
	global_load_dword v0, v161, s[10:11] sc1
	s_waitcnt vmcnt(0)
	v_cmp_lt_u32_e32 vcc, v0, v5
	s_and_saveexec_b64 s[10:11], vcc
	s_cbranch_execz .LBB0_662
	s_mov_b32 s20, 1
	s_branch .LBB0_655

; __device__ __forceinline__ unsigned xb_ld(unsigned* p)              { return __hip_atomic_load(p, __ATOMIC_RELAXED, __HIP_MEMORY_SCOPE_AGENT); }
; #define XB_SPIN(cond, bar) do { unsigned _sp = 0; while (cond) { \
;     if ((++_sp & 255u) == 0u) { if (xb_ld(&(bar)[XB_TMO])) break; if (_sp > XB_SPIN_CAP) { atomicAdd(&(bar)[XB_TMO], 1u); break; } } } } while (0)
; __device__ __forceinline__ void xcd_barrier(const XcdBarrier& b) {
;     ...
;             else XB_SPIN(xb_ld(&bar[XB_TOPGEN]) == tg, bar);
.LBB0_657:
	v_readlane_b32 s24, v253, 60
	v_readlane_b32 s25, v253, 61
	s_add_i32 s20, s20, 1
	s_mov_b64 s[46:47], -1
	s_nop 2
	global_load_dword v0, v161, s[24:25] sc1
	s_waitcnt vmcnt(0)
	v_cmp_ge_u32_e32 vcc, v0, v5
	s_orn2_b64 s[34:35], vcc, exec
	s_branch .LBB0_654

; __device__ __forceinline__ unsigned xb_ld(unsigned* p)              { return __hip_atomic_load(p, __ATOMIC_RELAXED, __HIP_MEMORY_SCOPE_AGENT); }
; __device__ __forceinline__ unsigned xb_add(unsigned* p, unsigned v) { return __hip_atomic_fetch_add(p, v, __ATOMIC_RELAXED, __HIP_MEMORY_SCOPE_AGENT); }
; #define XB_SPIN(cond, bar) do { unsigned _sp = 0; while (cond) { \
;     if ((++_sp & 255u) == 0u) { if (xb_ld(&(bar)[XB_TMO])) break; if (_sp > XB_SPIN_CAP) { atomicAdd(&(bar)[XB_TMO], 1u); break; } } } } while (0)
; __device__ __forceinline__ void xcd_barrier(const XcdBarrier& b) {
;     ...
;             const unsigned og = xb_add(&bar[XB_TOP], 1u);
;             const unsigned tg = og / nx;
;             if (og + 1u == (tg + 1u) * nx) xb_add(&bar[XB_TOPGEN], 1u);
;             else XB_SPIN(xb_ld(&bar[XB_TOPGEN]) == tg, bar);
.LBB0_812:
	s_or_b64 exec, exec, s[10:11]
	s_waitcnt vmcnt(0)
	v_readfirstlane_b32 s8, v2
	v_cvt_f32_u32_e32 v2, v0
	v_sub_u32_e32 v3, 0, v0
	v_add_u32_e32 v1, s8, v1
	v_readlane_b32 s8, v253, 62
	v_rcp_iflag_f32_e32 v2, v2
	v_readlane_b32 s9, v253, 63
	s_mov_b64 s[10:11], -1
	v_mul_f32_e32 v2, 0x4f7ffffe, v2
	v_cvt_u32_f32_e32 v2, v2
	v_mul_lo_u32 v3, v3, v2
	v_mul_hi_u32 v3, v2, v3
	v_add_u32_e32 v2, v2, v3
	v_mul_hi_u32 v2, v1, v2
	v_mul_lo_u32 v3, v2, v0
	v_sub_u32_e32 v3, v1, v3
	v_cmp_ge_u32_e32 vcc, v3, v0
	v_add_u32_e32 v4, 1, v2
	v_add_u32_e32 v1, 1, v1
	v_cndmask_b32_e32 v2, v2, v4, vcc
	v_sub_u32_e32 v4, v3, v0
	v_cndmask_b32_e32 v3, v3, v4, vcc
	v_cmp_ge_u32_e32 vcc, v3, v0
	v_add_u32_e32 v3, 1, v2
	s_nop 0
	v_cndmask_b32_e32 v2, v2, v3, vcc
	v_mul_lo_u32 v3, v0, v2
	v_add_u32_e32 v0, v3, v0
	v_cmp_ne_u32_e32 vcc, v1, v0
	v_mov_b32_e32 v5, v0
	v_mov_b64_e32 v[0:1], s[8:9]
	s_and_saveexec_b64 s[8:9], vcc
	s_cbranch_execz .LBB0_824
	v_readlane_b32 s10, v253, 60
	v_readlane_b32 s11, v253, 61
	s_mov_b64 s[12:13], 0
	s_nop 3
	global_load_dword v0, v161, s[10:11] sc1
	s_waitcnt vmcnt(0)
	v_cmp_lt_u32_e32 vcc, v0, v5
	s_and_saveexec_b64 s[10:11], vcc
	s_cbranch_execz .LBB0_823
	s_mov_b32 s20, 1
	s_branch .LBB0_816

; __device__ __forceinline__ unsigned xb_ld(unsigned* p)              { return __hip_atomic_load(p, __ATOMIC_RELAXED, __HIP_MEMORY_SCOPE_AGENT); }
; __device__ __forceinline__ unsigned xb_add(unsigned* p, unsigned v) { return __hip_atomic_fetch_add(p, v, __ATOMIC_RELAXED, __HIP_MEMORY_SCOPE_AGENT); }
; #define XB_SPIN(cond, bar) do { unsigned _sp = 0; while (cond) { \
;     if ((++_sp & 255u) == 0u) { if (xb_ld(&(bar)[XB_TMO])) break; if (_sp > XB_SPIN_CAP) { atomicAdd(&(bar)[XB_TMO], 1u); break; } } } } while (0)
; __device__ __forceinline__ void xcd_barrier(const XcdBarrier& b) {
;     ...
;             const unsigned og = xb_add(&bar[XB_TOP], 1u);
;             const unsigned tg = og / nx;
;             if (og + 1u == (tg + 1u) * nx) xb_add(&bar[XB_TOPGEN], 1u);
;             else XB_SPIN(xb_ld(&bar[XB_TOPGEN]) == tg, bar);
.LBB0_893:
	s_or_b64 exec, exec, s[8:9]
	s_waitcnt vmcnt(0)
	v_readfirstlane_b32 s6, v2
	v_cvt_f32_u32_e32 v2, v0
	v_sub_u32_e32 v3, 0, v0
	v_add_u32_e32 v1, s6, v1
	v_readlane_b32 s6, v253, 62
	v_rcp_iflag_f32_e32 v2, v2
	v_readlane_b32 s7, v253, 63
	s_mov_b64 s[8:9], -1
	v_mul_f32_e32 v2, 0x4f7ffffe, v2
	v_cvt_u32_f32_e32 v2, v2
	v_mul_lo_u32 v3, v3, v2
	v_mul_hi_u32 v3, v2, v3
	v_add_u32_e32 v2, v2, v3
	v_mul_hi_u32 v2, v1, v2
	v_mul_lo_u32 v3, v2, v0
	v_sub_u32_e32 v3, v1, v3
	v_cmp_ge_u32_e32 vcc, v3, v0
	v_add_u32_e32 v4, 1, v2
	v_add_u32_e32 v1, 1, v1
	v_cndmask_b32_e32 v2, v2, v4, vcc
	v_sub_u32_e32 v4, v3, v0
	v_cndmask_b32_e32 v3, v3, v4, vcc
	v_cmp_ge_u32_e32 vcc, v3, v0
	v_add_u32_e32 v3, 1, v2
	s_nop 0
	v_cndmask_b32_e32 v2, v2, v3, vcc
	v_mul_lo_u32 v3, v0, v2
	v_add_u32_e32 v0, v3, v0
	v_cmp_ne_u32_e32 vcc, v1, v0
	v_mov_b32_e32 v5, v0
	v_mov_b64_e32 v[0:1], s[6:7]
	s_and_saveexec_b64 s[6:7], vcc
	s_cbranch_execz .LBB0_905
	v_readlane_b32 s8, v253, 60
	v_readlane_b32 s9, v253, 61
	s_mov_b64 s[10:11], 0
	s_nop 3
	global_load_dword v0, v161, s[8:9] sc1
	s_waitcnt vmcnt(0)
	v_cmp_lt_u32_e32 vcc, v0, v5
	s_and_saveexec_b64 s[8:9], vcc
	s_cbranch_execz .LBB0_904
	s_mov_b32 s15, 1
	s_branch .LBB0_897

; __device__ __forceinline__ unsigned xb_ld(unsigned* p)              { return __hip_atomic_load(p, __ATOMIC_RELAXED, __HIP_MEMORY_SCOPE_AGENT); }
; #define XB_SPIN(cond, bar) do { unsigned _sp = 0; while (cond) { \
;     if ((++_sp & 255u) == 0u) { if (xb_ld(&(bar)[XB_TMO])) break; if (_sp > XB_SPIN_CAP) { atomicAdd(&(bar)[XB_TMO], 1u); break; } } } } while (0)
; __device__ __forceinline__ void xcd_barrier(const XcdBarrier& b) {
;     ...
;             else XB_SPIN(xb_ld(&bar[XB_TOPGEN]) == tg, bar);
.LBB0_899:
	v_readlane_b32 s24, v253, 60
	v_readlane_b32 s25, v253, 61
	s_add_i32 s15, s15, 1
	s_mov_b64 s[46:47], -1
	s_nop 2
	global_load_dword v0, v161, s[24:25] sc1
	s_waitcnt vmcnt(0)
	v_cmp_ge_u32_e32 vcc, v0, v5
	s_orn2_b64 s[34:35], vcc, exec
	s_branch .LBB0_896

; __device__ __forceinline__ unsigned xb_ld(unsigned* p)              { return __hip_atomic_load(p, __ATOMIC_RELAXED, __HIP_MEMORY_SCOPE_AGENT); }
; __device__ __forceinline__ unsigned xb_add(unsigned* p, unsigned v) { return __hip_atomic_fetch_add(p, v, __ATOMIC_RELAXED, __HIP_MEMORY_SCOPE_AGENT); }
; #define XB_SPIN(cond, bar) do { unsigned _sp = 0; while (cond) { \
;     if ((++_sp & 255u) == 0u) { if (xb_ld(&(bar)[XB_TMO])) break; if (_sp > XB_SPIN_CAP) { atomicAdd(&(bar)[XB_TMO], 1u); break; } } } } while (0)
; __device__ __forceinline__ void xcd_barrier(const XcdBarrier& b) {
;     ...
;             const unsigned og = xb_add(&bar[XB_TOP], 1u);
;             const unsigned tg = og / nx;
;             if (og + 1u == (tg + 1u) * nx) xb_add(&bar[XB_TOPGEN], 1u);
;             else XB_SPIN(xb_ld(&bar[XB_TOPGEN]) == tg, bar);
.LBB0_1117:
	s_or_b64 exec, exec, s[8:9]
	s_waitcnt vmcnt(0)
	v_readfirstlane_b32 s6, v2
	v_cvt_f32_u32_e32 v2, v0
	v_sub_u32_e32 v3, 0, v0
	v_add_u32_e32 v1, s6, v1
	v_readlane_b32 s6, v253, 62
	v_rcp_iflag_f32_e32 v2, v2
	v_readlane_b32 s7, v253, 63
	s_mov_b64 s[8:9], -1
	v_mul_f32_e32 v2, 0x4f7ffffe, v2
	v_cvt_u32_f32_e32 v2, v2
	v_mul_lo_u32 v3, v3, v2
	v_mul_hi_u32 v3, v2, v3
	v_add_u32_e32 v2, v2, v3
	v_mul_hi_u32 v2, v1, v2
	v_mul_lo_u32 v3, v2, v0
	v_sub_u32_e32 v3, v1, v3
	v_cmp_ge_u32_e32 vcc, v3, v0
	v_add_u32_e32 v4, 1, v2
	v_add_u32_e32 v1, 1, v1
	v_cndmask_b32_e32 v2, v2, v4, vcc
	v_sub_u32_e32 v4, v3, v0
	v_cndmask_b32_e32 v3, v3, v4, vcc
	v_cmp_ge_u32_e32 vcc, v3, v0
	v_add_u32_e32 v3, 1, v2
	s_nop 0
	v_cndmask_b32_e32 v2, v2, v3, vcc
	v_mul_lo_u32 v3, v0, v2
	v_add_u32_e32 v0, v3, v0
	v_cmp_ne_u32_e32 vcc, v1, v0
	v_mov_b32_e32 v5, v0
	v_mov_b64_e32 v[0:1], s[6:7]
	s_and_saveexec_b64 s[6:7], vcc
	s_cbranch_execz .LBB0_1129
	v_readlane_b32 s8, v253, 60
	v_readlane_b32 s9, v253, 61
	s_mov_b64 s[10:11], 0
	s_nop 3
	global_load_dword v0, v161, s[8:9] sc1
	s_waitcnt vmcnt(0)
	v_cmp_lt_u32_e32 vcc, v0, v5
	s_and_saveexec_b64 s[8:9], vcc
	s_cbranch_execz .LBB0_1128
	s_mov_b64 s[38:39], s[34:35]
	s_mov_b32 s15, 1
	s_branch .LBB0_1121

; __device__ __forceinline__ unsigned xb_ld(unsigned* p)              { return __hip_atomic_load(p, __ATOMIC_RELAXED, __HIP_MEMORY_SCOPE_AGENT); }
; __device__ __forceinline__ unsigned xb_add(unsigned* p, unsigned v) { return __hip_atomic_fetch_add(p, v, __ATOMIC_RELAXED, __HIP_MEMORY_SCOPE_AGENT); }
; #define XB_SPIN(cond, bar) do { unsigned _sp = 0; while (cond) { \
;     if ((++_sp & 255u) == 0u) { if (xb_ld(&(bar)[XB_TMO])) break; if (_sp > XB_SPIN_CAP) { atomicAdd(&(bar)[XB_TMO], 1u); break; } } } } while (0)
; __device__ __forceinline__ void xcd_barrier(const XcdBarrier& b) {
;     ...
;             const unsigned og = xb_add(&bar[XB_TOP], 1u);
;             const unsigned tg = og / nx;
;             if (og + 1u == (tg + 1u) * nx) xb_add(&bar[XB_TOPGEN], 1u);
;             else XB_SPIN(xb_ld(&bar[XB_TOPGEN]) == tg, bar);
.LBB0_1177:
	s_or_b64 exec, exec, s[10:11]
	s_waitcnt vmcnt(0)
	v_readfirstlane_b32 s8, v2
	v_cvt_f32_u32_e32 v2, v0
	v_sub_u32_e32 v3, 0, v0
	v_add_u32_e32 v1, s8, v1
	v_readlane_b32 s8, v253, 62
	v_rcp_iflag_f32_e32 v2, v2
	v_readlane_b32 s9, v253, 63
	s_mov_b64 s[10:11], -1
	v_mul_f32_e32 v2, 0x4f7ffffe, v2
	v_cvt_u32_f32_e32 v2, v2
	v_mul_lo_u32 v3, v3, v2
	v_mul_hi_u32 v3, v2, v3
	v_add_u32_e32 v2, v2, v3
	v_mul_hi_u32 v2, v1, v2
	v_mul_lo_u32 v3, v2, v0
	v_sub_u32_e32 v3, v1, v3
	v_cmp_ge_u32_e32 vcc, v3, v0
	v_add_u32_e32 v4, 1, v2
	v_add_u32_e32 v1, 1, v1
	v_cndmask_b32_e32 v2, v2, v4, vcc
	v_sub_u32_e32 v4, v3, v0
	v_cndmask_b32_e32 v3, v3, v4, vcc
	v_cmp_ge_u32_e32 vcc, v3, v0
	v_add_u32_e32 v3, 1, v2
	s_nop 0
	v_cndmask_b32_e32 v2, v2, v3, vcc
	v_mul_lo_u32 v3, v0, v2
	v_add_u32_e32 v0, v3, v0
	v_cmp_ne_u32_e32 vcc, v1, v0
	v_mov_b32_e32 v5, v0
	v_mov_b64_e32 v[0:1], s[8:9]
	s_and_saveexec_b64 s[8:9], vcc
	s_cbranch_execz .LBB0_1189
	v_readlane_b32 s10, v253, 60
	v_readlane_b32 s11, v253, 61
	s_mov_b64 s[12:13], 0
	s_nop 3
	global_load_dword v0, v161, s[10:11] sc1
	s_waitcnt vmcnt(0)
	v_cmp_lt_u32_e32 vcc, v0, v5
	s_and_saveexec_b64 s[10:11], vcc
	s_cbranch_execz .LBB0_1188
	s_mov_b32 s15, 1
	s_branch .LBB0_1181

; __device__ __forceinline__ unsigned xb_ld(unsigned* p)              { return __hip_atomic_load(p, __ATOMIC_RELAXED, __HIP_MEMORY_SCOPE_AGENT); }
; #define XB_SPIN(cond, bar) do { unsigned _sp = 0; while (cond) { \
;     if ((++_sp & 255u) == 0u) { if (xb_ld(&(bar)[XB_TMO])) break; if (_sp > XB_SPIN_CAP) { atomicAdd(&(bar)[XB_TMO], 1u); break; } } } } while (0)
; __device__ __forceinline__ void xcd_barrier(const XcdBarrier& b) {
;     ...
;             else XB_SPIN(xb_ld(&bar[XB_TOPGEN]) == tg, bar);
.LBB0_1183:
	v_readlane_b32 s24, v253, 60
	v_readlane_b32 s25, v253, 61
	s_add_i32 s15, s15, 1
	s_mov_b64 s[50:51], -1
	s_nop 2
	global_load_dword v0, v161, s[24:25] sc1
	s_waitcnt vmcnt(0)
	v_cmp_ge_u32_e32 vcc, v0, v5
	s_orn2_b64 s[46:47], vcc, exec
	s_branch .LBB0_1180

; __device__ __forceinline__ unsigned xb_ld(unsigned* p)              { return __hip_atomic_load(p, __ATOMIC_RELAXED, __HIP_MEMORY_SCOPE_AGENT); }
; __device__ __forceinline__ unsigned xb_add(unsigned* p, unsigned v) { return __hip_atomic_fetch_add(p, v, __ATOMIC_RELAXED, __HIP_MEMORY_SCOPE_AGENT); }
; #define XB_SPIN(cond, bar) do { unsigned _sp = 0; while (cond) { \
;     if ((++_sp & 255u) == 0u) { if (xb_ld(&(bar)[XB_TMO])) break; if (_sp > XB_SPIN_CAP) { atomicAdd(&(bar)[XB_TMO], 1u); break; } } } } while (0)
; __device__ __forceinline__ void xcd_barrier(const XcdBarrier& b) {
;     ...
;             const unsigned og = xb_add(&bar[XB_TOP], 1u);
;             const unsigned tg = og / nx;
;             if (og + 1u == (tg + 1u) * nx) xb_add(&bar[XB_TOPGEN], 1u);
;             else XB_SPIN(xb_ld(&bar[XB_TOPGEN]) == tg, bar);
.LBB0_1246:
	s_or_b64 exec, exec, s[12:13]
	s_waitcnt vmcnt(0)
	v_readfirstlane_b32 s10, v2
	v_cvt_f32_u32_e32 v2, v0
	v_sub_u32_e32 v3, 0, v0
	v_add_u32_e32 v1, s10, v1
	v_readlane_b32 s10, v253, 62
	v_rcp_iflag_f32_e32 v2, v2
	v_readlane_b32 s11, v253, 63
	s_mov_b64 s[12:13], -1
	v_mul_f32_e32 v2, 0x4f7ffffe, v2
	v_cvt_u32_f32_e32 v2, v2
	v_mul_lo_u32 v3, v3, v2
	v_mul_hi_u32 v3, v2, v3
	v_add_u32_e32 v2, v2, v3
	v_mul_hi_u32 v2, v1, v2
	v_mul_lo_u32 v3, v2, v0
	v_sub_u32_e32 v3, v1, v3
	v_cmp_ge_u32_e32 vcc, v3, v0
	v_add_u32_e32 v4, 1, v2
	v_add_u32_e32 v1, 1, v1
	v_cndmask_b32_e32 v2, v2, v4, vcc
	v_sub_u32_e32 v4, v3, v0
	v_cndmask_b32_e32 v3, v3, v4, vcc
	v_cmp_ge_u32_e32 vcc, v3, v0
	v_add_u32_e32 v3, 1, v2
	s_nop 0
	v_cndmask_b32_e32 v2, v2, v3, vcc
	v_mul_lo_u32 v3, v0, v2
	v_add_u32_e32 v0, v3, v0
	v_cmp_ne_u32_e32 vcc, v1, v0
	v_mov_b32_e32 v5, v0
	v_mov_b64_e32 v[0:1], s[10:11]
	s_and_saveexec_b64 s[10:11], vcc
	s_cbranch_execz .LBB0_1258
	v_readlane_b32 s12, v253, 60
	v_readlane_b32 s13, v253, 61
	s_mov_b64 s[34:35], 0
	s_nop 3
	global_load_dword v0, v161, s[12:13] sc1
	s_waitcnt vmcnt(0)
	v_cmp_lt_u32_e32 vcc, v0, v5
	s_and_saveexec_b64 s[12:13], vcc
	s_cbranch_execz .LBB0_1257
	s_mov_b32 s15, 1
	s_branch .LBB0_1250

; __device__ __forceinline__ unsigned xb_ld(unsigned* p)              { return __hip_atomic_load(p, __ATOMIC_RELAXED, __HIP_MEMORY_SCOPE_AGENT); }
; #define XB_SPIN(cond, bar) do { unsigned _sp = 0; while (cond) { \
;     if ((++_sp & 255u) == 0u) { if (xb_ld(&(bar)[XB_TMO])) break; if (_sp > XB_SPIN_CAP) { atomicAdd(&(bar)[XB_TMO], 1u); break; } } } } while (0)
; __device__ __forceinline__ void xcd_barrier(const XcdBarrier& b) {
;     ...
;             else XB_SPIN(xb_ld(&bar[XB_TOPGEN]) == tg, bar);
.LBB0_1252:
	v_readlane_b32 s24, v253, 60
	v_readlane_b32 s25, v253, 61
	s_add_i32 s15, s15, 1
	s_mov_b64 s[66:67], -1
	s_nop 2
	global_load_dword v0, v161, s[24:25] sc1
	s_waitcnt vmcnt(0)
	v_cmp_ge_u32_e32 vcc, v0, v5
	s_orn2_b64 s[50:51], vcc, exec
	s_branch .LBB0_1249

; __device__ __forceinline__ unsigned xb_ld(unsigned* p)              { return __hip_atomic_load(p, __ATOMIC_RELAXED, __HIP_MEMORY_SCOPE_AGENT); }
; __device__ __forceinline__ unsigned xb_add(unsigned* p, unsigned v) { return __hip_atomic_fetch_add(p, v, __ATOMIC_RELAXED, __HIP_MEMORY_SCOPE_AGENT); }
; #define XB_SPIN(cond, bar) do { unsigned _sp = 0; while (cond) { \
;     if ((++_sp & 255u) == 0u) { if (xb_ld(&(bar)[XB_TMO])) break; if (_sp > XB_SPIN_CAP) { atomicAdd(&(bar)[XB_TMO], 1u); break; } } } } while (0)
; __device__ __forceinline__ void xcd_barrier(const XcdBarrier& b) {
;     ...
;             const unsigned og = xb_add(&bar[XB_TOP], 1u);
;             const unsigned tg = og / nx;
;             if (og + 1u == (tg + 1u) * nx) xb_add(&bar[XB_TOPGEN], 1u);
;             else XB_SPIN(xb_ld(&bar[XB_TOPGEN]) == tg, bar);
.LBB0_1480:
	s_or_b64 exec, exec, s[8:9]
	s_waitcnt vmcnt(0)
	v_readfirstlane_b32 s6, v2
	v_cvt_f32_u32_e32 v2, v0
	v_sub_u32_e32 v3, 0, v0
	v_add_u32_e32 v1, s6, v1
	v_readlane_b32 s6, v253, 62
	v_rcp_iflag_f32_e32 v2, v2
	v_readlane_b32 s7, v253, 63
	s_mov_b64 s[8:9], -1
	v_mul_f32_e32 v2, 0x4f7ffffe, v2
	v_cvt_u32_f32_e32 v2, v2
	v_mul_lo_u32 v3, v3, v2
	v_mul_hi_u32 v3, v2, v3
	v_add_u32_e32 v2, v2, v3
	v_mul_hi_u32 v2, v1, v2
	v_mul_lo_u32 v3, v2, v0
	v_sub_u32_e32 v3, v1, v3
	v_cmp_ge_u32_e32 vcc, v3, v0
	v_add_u32_e32 v4, 1, v2
	v_add_u32_e32 v1, 1, v1
	v_cndmask_b32_e32 v2, v2, v4, vcc
	v_sub_u32_e32 v4, v3, v0
	v_cndmask_b32_e32 v3, v3, v4, vcc
	v_cmp_ge_u32_e32 vcc, v3, v0
	v_add_u32_e32 v3, 1, v2
	s_nop 0
	v_cndmask_b32_e32 v2, v2, v3, vcc
	v_mul_lo_u32 v3, v0, v2
	v_add_u32_e32 v0, v3, v0
	v_cmp_ne_u32_e32 vcc, v1, v0
	v_mov_b32_e32 v5, v0
	v_mov_b64_e32 v[0:1], s[6:7]
	s_and_saveexec_b64 s[6:7], vcc
	s_cbranch_execz .LBB0_1492
	v_readlane_b32 s8, v253, 60
	v_readlane_b32 s9, v253, 61
	s_mov_b64 s[10:11], 0
	s_nop 3
	global_load_dword v0, v161, s[8:9] sc1
	s_waitcnt vmcnt(0)
	v_cmp_lt_u32_e32 vcc, v0, v5
	s_and_saveexec_b64 s[8:9], vcc
	s_cbranch_execz .LBB0_1491
	s_mov_b32 s20, 1
	s_branch .LBB0_1484
